# merge-GEMM loop: dropped redundant post-barrier lgkmcnt(0)
# speedup vs baseline: 1.0079x; 1.0014x over previous
.LBB0_1002:
	s_waitcnt lgkmcnt(0)
	s_barrier
	s_setprio 1
	v_mfma_f32_16x16x32_bf16 v[126:129], v[146:149], v[186:189], v[126:129]
	v_mfma_f32_16x16x32_bf16 v[122:125], v[154:157], v[186:189], v[122:125]
	v_mfma_f32_16x16x32_bf16 v[110:113], v[146:149], v[178:181], v[110:113]
	v_mfma_f32_16x16x32_bf16 v[106:109], v[154:157], v[178:181], v[106:109]
	v_mfma_f32_16x16x32_bf16 v[94:97], v[146:149], v[170:173], v[94:97]
	v_mfma_f32_16x16x32_bf16 v[90:93], v[154:157], v[170:173], v[90:93]
	v_mfma_f32_16x16x32_bf16 v[78:81], v[146:149], v[162:165], v[78:81]
	v_mfma_f32_16x16x32_bf16 v[74:77], v[154:157], v[162:165], v[74:77]
	v_mfma_f32_16x16x32_bf16 v[126:129], v[150:153], v[190:193], v[126:129]
	v_mfma_f32_16x16x32_bf16 v[122:125], v[158:161], v[190:193], v[122:125]
	v_mfma_f32_16x16x32_bf16 v[110:113], v[150:153], v[182:185], v[110:113]
	v_mfma_f32_16x16x32_bf16 v[106:109], v[158:161], v[182:185], v[106:109]
	v_mfma_f32_16x16x32_bf16 v[94:97], v[150:153], v[174:177], v[94:97]
	v_mfma_f32_16x16x32_bf16 v[90:93], v[158:161], v[174:177], v[90:93]
	v_mfma_f32_16x16x32_bf16 v[78:81], v[150:153], v[166:169], v[78:81]
	v_mfma_f32_16x16x32_bf16 v[74:77], v[158:161], v[166:169], v[74:77]
	s_setprio 0
	s_setprio 1
	v_mfma_f32_16x16x32_bf16 v[118:121], v[130:133], v[186:189], v[118:121]
	v_mfma_f32_16x16x32_bf16 v[114:117], v[138:141], v[186:189], v[114:117]
	v_mfma_f32_16x16x32_bf16 v[102:105], v[130:133], v[178:181], v[102:105]
	v_mfma_f32_16x16x32_bf16 v[98:101], v[138:141], v[178:181], v[98:101]
	v_mfma_f32_16x16x32_bf16 v[86:89], v[130:133], v[170:173], v[86:89]
	v_mfma_f32_16x16x32_bf16 v[82:85], v[138:141], v[170:173], v[82:85]
	v_mfma_f32_16x16x32_bf16 v[70:73], v[130:133], v[162:165], v[70:73]
	v_mfma_f32_16x16x32_bf16 v[66:69], v[138:141], v[162:165], v[66:69]
	v_mfma_f32_16x16x32_bf16 v[118:121], v[134:137], v[190:193], v[118:121]
	v_mfma_f32_16x16x32_bf16 v[114:117], v[142:145], v[190:193], v[114:117]
	v_mfma_f32_16x16x32_bf16 v[102:105], v[134:137], v[182:185], v[102:105]
	v_mfma_f32_16x16x32_bf16 v[98:101], v[142:145], v[182:185], v[98:101]
	v_mfma_f32_16x16x32_bf16 v[86:89], v[134:137], v[174:177], v[86:89]
	v_mfma_f32_16x16x32_bf16 v[82:85], v[142:145], v[174:177], v[82:85]
	v_mfma_f32_16x16x32_bf16 v[70:73], v[134:137], v[166:169], v[70:73]
	v_mfma_f32_16x16x32_bf16 v[66:69], v[142:145], v[166:169], v[66:69]
	s_setprio 0
	s_barrier
	s_cmp_lg_u32 s22, 7
	s_cbranch_scc1 .LBB0_997
	s_cmp_gt_u32 s65, 7
	s_waitcnt vmcnt(6)
	v_cvt_f32_ubyte3_e32 v131, v206
	v_cvt_f32_ubyte2_e32 v130, v206
	v_cvt_f32_ubyte1_e32 v133, v206
	v_cvt_f32_ubyte0_e32 v132, v206
	s_cselect_b64 s[16:17], -1, 0
	v_pk_mul_f32 v[134:135], v[132:133], s[20:21] op_sel_hi:[1,0]
	v_pk_mul_f32 v[136:137], v[130:131], s[20:21] op_sel_hi:[1,0]
	v_cvt_f32_ubyte1_e32 v133, v207
	v_cvt_f32_ubyte0_e32 v132, v207
	v_cvt_f32_ubyte3_e32 v131, v207
	v_cvt_f32_ubyte2_e32 v130, v207
	v_pk_mul_f32 v[130:131], v[130:131], s[20:21] op_sel_hi:[1,0]
	v_pk_mul_f32 v[132:133], v[132:133], s[20:21] op_sel_hi:[1,0]
	v_pk_mul_f32 v[128:129], v[136:137], v[128:129]
	v_pk_mul_f32 v[126:127], v[134:135], v[126:127]
	s_mov_b64 s[22:23], -1
	s_and_b64 vcc, exec, s[16:17]
	s_cbranch_vccz .LBB0_1005
	v_pk_add_f32 v[64:65], v[64:65], v[128:129]
	v_pk_add_f32 v[62:63], v[62:63], v[126:127]
	v_pk_fma_f32 v[60:61], v[130:131], v[124:125], v[60:61]
	v_pk_fma_f32 v[58:59], v[132:133], v[122:123], v[58:59]
	s_mov_b64 s[22:23], 0
